# adds: P4 tail_gemm re-tiled to 64x64 sub-tiles with all operand loads in flight
# speedup vs baseline: 1.0541x; 1.0057x over previous
.LBB0_1124:
	s_ashr_i32 s1, s36, 4
	s_add_i32 s1, s1, s33
	s_ashr_i32 s2, s1, 31
	s_lshr_b32 s2, s2, 29
	s_add_i32 s2, s1, s2
	s_ashr_i32 s3, s2, 3
	s_and_b32 s2, s2, -8
	s_and_b32 s0, s7, 0xf0
	s_sub_i32 s1, s1, s2
	s_cmp_lt_i32 s1, 0
	s_cselect_b32 s2, 35, 34
	s_mul_i32 s1, s1, s2
	s_add_i32 s1, s1, s3
	s_ashr_i32 s2, s1, 31
	s_lshr_b32 s2, s2, 27
	s_add_i32 s2, s1, s2
	s_ashr_i32 s3, s2, 5
	s_lshl_b32 s3, s3, 3
	s_sub_i32 s37, 0x44, s3
	s_min_i32 s38, s37, 8
	s_abs_i32 s37, s38
	v_cvt_f32_u32_e32 v0, s37
	s_sub_i32 s40, 0, s37
	s_andn2_b32 s2, s2, 31
	s_sub_i32 s1, s1, s2
	v_rcp_iflag_f32_e32 v0, v0
	s_abs_i32 s2, s1
	s_xor_b32 s39, s1, s38
	s_ashr_i32 s39, s39, 31
	v_mul_f32_e32 v0, 0x4f7ffffe, v0
	v_cvt_u32_f32_e32 v0, v0
	v_mov_b32_e32 v2, v183
	v_mov_b32_e32 v3, v183
	v_mov_b32_e32 v4, 0
	v_readfirstlane_b32 s41, v0
	s_mul_i32 s40, s40, s41
	s_mul_hi_u32 s40, s41, s40
	s_add_i32 s41, s41, s40
	s_mul_hi_u32 s40, s2, s41
	s_mul_i32 s41, s40, s37
	s_sub_i32 s2, s2, s41
	s_add_i32 s42, s40, 1
	s_sub_i32 s41, s2, s37
	s_cmp_ge_u32 s2, s37
	s_cselect_b32 s40, s42, s40
	s_cselect_b32 s2, s41, s2
	s_add_i32 s41, s40, 1
	s_cmp_ge_u32 s2, s37
	s_cselect_b32 s2, s41, s40
	s_xor_b32 s2, s2, s39
	s_sub_i32 s37, s2, s39
	s_mul_i32 s38, s37, s38
	s_sub_i32 s1, s1, s38
	s_add_i32 s3, s3, s1
	s_lshl_b32 s38, s3, 8
	s_mov_b32 s44, 0x2300000
	s_mov_b32 s45, 0
	s_mov_b32 s56, 0x1d00000
	s_mov_b32 s57, 0
	s_mov_b32 s46, 0x2308000
	s_mov_b32 s47, 0
	s_mov_b32 s58, 0x1d08000
	s_mov_b32 s59, 0
	s_mov_b32 s48, 0x2310000
	s_mov_b32 s49, 0
	s_mov_b32 s60, 0x1d10000
	s_mov_b32 s61, 0
	s_mov_b32 s50, 0x2318000
	s_mov_b32 s51, 0
	s_mov_b32 s62, 0x1d18000
	s_mov_b32 s63, 0
	v_or_b32_e32 v0, s38, v179
	s_and_b32 s64, s7, 0xc0
	v_or_b32_e32 v0, s64, v0
	s_waitcnt vmcnt(0) lgkmcnt(0)
	v_ashrrev_i32_e32 v1, 31, v0
	v_lshlrev_b64 v[0:1], 11, v[0:1]
	v_lshl_add_u64 v[222:223], v[64:65], 0, v[0:1]
	v_lshl_or_b32 v0, s2, 8, v179
	s_lshl_b32 s0, s39, 8
	v_subrev_u32_e32 v0, s0, v0
	s_and_b32 s64, s7, 0x30
	s_lshl_b32 s64, s64, 2
	v_add_u32_e32 v0, s64, v0
	v_ashrrev_i32_e32 v1, 31, v0
	v_lshlrev_b64 v[0:1], 11, v[0:1]
	v_lshl_add_u64 v[224:225], v[64:65], 0, v[0:1]
	v_lshl_add_u64 v[226:227], v[222:223], 0, s[44:45]
	v_lshl_add_u64 v[234:235], v[224:225], 0, s[56:57]
	v_lshl_add_u64 v[228:229], v[222:223], 0, s[46:47]
	v_lshl_add_u64 v[236:237], v[224:225], 0, s[58:59]
	v_lshl_add_u64 v[230:231], v[222:223], 0, s[48:49]
	v_lshl_add_u64 v[238:239], v[224:225], 0, s[60:61]
	v_lshl_add_u64 v[232:233], v[222:223], 0, s[50:51]
	v_lshl_add_u64 v[240:241], v[224:225], 0, s[62:63]
	global_load_dwordx4 v[0:3], v[226:227], off
	global_load_dwordx4 v[4:7], v[226:227], off offset:64
	global_load_dwordx4 v[16:19], v[228:229], off
	global_load_dwordx4 v[20:23], v[228:229], off offset:64
	global_load_dwordx4 v[32:35], v[230:231], off
	global_load_dwordx4 v[36:39], v[230:231], off offset:64
	global_load_dwordx4 v[48:51], v[232:233], off
	global_load_dwordx4 v[52:55], v[232:233], off offset:64
	global_load_dwordx4 v[136:139], v[234:235], off
	global_load_dwordx4 v[140:143], v[234:235], off offset:64
	global_load_dwordx4 v[152:155], v[236:237], off
	global_load_dwordx4 v[156:159], v[236:237], off offset:64
	global_load_dwordx4 v[168:171], v[238:239], off
	global_load_dwordx4 v[172:175], v[238:239], off offset:64
	global_load_dwordx4 v[192:195], v[240:241], off
	global_load_dwordx4 v[196:199], v[240:241], off offset:64
	global_load_dwordx4 v[8:11], v[226:227], off offset:128
	global_load_dwordx4 v[12:15], v[226:227], off offset:192
	global_load_dwordx4 v[24:27], v[228:229], off offset:128
	global_load_dwordx4 v[28:31], v[228:229], off offset:192
	global_load_dwordx4 v[40:43], v[230:231], off offset:128
	global_load_dwordx4 v[44:47], v[230:231], off offset:192
	global_load_dwordx4 v[56:59], v[232:233], off offset:128
	global_load_dwordx4 v[60:63], v[232:233], off offset:192
	global_load_dwordx4 v[144:147], v[234:235], off offset:128
	global_load_dwordx4 v[148:151], v[234:235], off offset:192
	global_load_dwordx4 v[160:163], v[236:237], off offset:128
	global_load_dwordx4 v[164:167], v[236:237], off offset:192
	global_load_dwordx4 v[184:187], v[238:239], off offset:128
	global_load_dwordx4 v[188:191], v[238:239], off offset:192
	global_load_dwordx4 v[200:203], v[240:241], off offset:128
	global_load_dwordx4 v[204:207], v[240:241], off offset:192
	s_waitcnt vmcnt(16)
	v_mfma_f32_16x16x32_bf16 v[72:75], v[0:3], v[136:139], 0
	v_mfma_f32_16x16x32_bf16 v[76:79], v[0:3], v[152:155], 0
	v_mfma_f32_16x16x32_bf16 v[80:83], v[0:3], v[168:171], 0
	v_mfma_f32_16x16x32_bf16 v[84:87], v[0:3], v[192:195], 0
	v_mfma_f32_16x16x32_bf16 v[88:91], v[16:19], v[136:139], 0
	v_mfma_f32_16x16x32_bf16 v[92:95], v[16:19], v[152:155], 0
	v_mfma_f32_16x16x32_bf16 v[96:99], v[16:19], v[168:171], 0
	v_mfma_f32_16x16x32_bf16 v[100:103], v[16:19], v[192:195], 0
	v_mfma_f32_16x16x32_bf16 v[104:107], v[32:35], v[136:139], 0
	v_mfma_f32_16x16x32_bf16 v[108:111], v[32:35], v[152:155], 0
	v_mfma_f32_16x16x32_bf16 v[112:115], v[32:35], v[168:171], 0
	v_mfma_f32_16x16x32_bf16 v[116:119], v[32:35], v[192:195], 0
	v_mfma_f32_16x16x32_bf16 v[120:123], v[48:51], v[136:139], 0
	v_mfma_f32_16x16x32_bf16 v[124:127], v[48:51], v[152:155], 0
	v_mfma_f32_16x16x32_bf16 v[128:131], v[48:51], v[168:171], 0
	v_mfma_f32_16x16x32_bf16 v[132:135], v[48:51], v[192:195], 0
	v_mfma_f32_16x16x32_bf16 v[72:75], v[4:7], v[140:143], v[72:75]
	v_mfma_f32_16x16x32_bf16 v[76:79], v[4:7], v[156:159], v[76:79]
	v_mfma_f32_16x16x32_bf16 v[80:83], v[4:7], v[172:175], v[80:83]
	v_mfma_f32_16x16x32_bf16 v[84:87], v[4:7], v[196:199], v[84:87]
	v_mfma_f32_16x16x32_bf16 v[88:91], v[20:23], v[140:143], v[88:91]
	v_mfma_f32_16x16x32_bf16 v[92:95], v[20:23], v[156:159], v[92:95]
	v_mfma_f32_16x16x32_bf16 v[96:99], v[20:23], v[172:175], v[96:99]
	v_mfma_f32_16x16x32_bf16 v[100:103], v[20:23], v[196:199], v[100:103]
	v_mfma_f32_16x16x32_bf16 v[104:107], v[36:39], v[140:143], v[104:107]
	v_mfma_f32_16x16x32_bf16 v[108:111], v[36:39], v[156:159], v[108:111]
	v_mfma_f32_16x16x32_bf16 v[112:115], v[36:39], v[172:175], v[112:115]
	v_mfma_f32_16x16x32_bf16 v[116:119], v[36:39], v[196:199], v[116:119]
	v_mfma_f32_16x16x32_bf16 v[120:123], v[52:55], v[140:143], v[120:123]
	v_mfma_f32_16x16x32_bf16 v[124:127], v[52:55], v[156:159], v[124:127]
	v_mfma_f32_16x16x32_bf16 v[128:131], v[52:55], v[172:175], v[128:131]
	v_mfma_f32_16x16x32_bf16 v[132:135], v[52:55], v[196:199], v[132:135]
	s_waitcnt vmcnt(0)
	v_mfma_f32_16x16x32_bf16 v[72:75], v[8:11], v[144:147], v[72:75]
	v_mfma_f32_16x16x32_bf16 v[76:79], v[8:11], v[160:163], v[76:79]
	v_mfma_f32_16x16x32_bf16 v[80:83], v[8:11], v[184:187], v[80:83]
	v_mfma_f32_16x16x32_bf16 v[84:87], v[8:11], v[200:203], v[84:87]
	v_mfma_f32_16x16x32_bf16 v[88:91], v[24:27], v[144:147], v[88:91]
	v_mfma_f32_16x16x32_bf16 v[92:95], v[24:27], v[160:163], v[92:95]
	v_mfma_f32_16x16x32_bf16 v[96:99], v[24:27], v[184:187], v[96:99]
	v_mfma_f32_16x16x32_bf16 v[100:103], v[24:27], v[200:203], v[100:103]
	v_mfma_f32_16x16x32_bf16 v[104:107], v[40:43], v[144:147], v[104:107]
	v_mfma_f32_16x16x32_bf16 v[108:111], v[40:43], v[160:163], v[108:111]
	v_mfma_f32_16x16x32_bf16 v[112:115], v[40:43], v[184:187], v[112:115]
	v_mfma_f32_16x16x32_bf16 v[116:119], v[40:43], v[200:203], v[116:119]
	v_mfma_f32_16x16x32_bf16 v[120:123], v[56:59], v[144:147], v[120:123]
	v_mfma_f32_16x16x32_bf16 v[124:127], v[56:59], v[160:163], v[124:127]
	v_mfma_f32_16x16x32_bf16 v[128:131], v[56:59], v[184:187], v[128:131]
	v_mfma_f32_16x16x32_bf16 v[132:135], v[56:59], v[200:203], v[132:135]
	v_mfma_f32_16x16x32_bf16 v[72:75], v[12:15], v[148:151], v[72:75]
	v_mfma_f32_16x16x32_bf16 v[76:79], v[12:15], v[164:167], v[76:79]
	v_mfma_f32_16x16x32_bf16 v[80:83], v[12:15], v[188:191], v[80:83]
	v_mfma_f32_16x16x32_bf16 v[84:87], v[12:15], v[204:207], v[84:87]
	v_mfma_f32_16x16x32_bf16 v[88:91], v[28:31], v[148:151], v[88:91]
	v_mfma_f32_16x16x32_bf16 v[92:95], v[28:31], v[164:167], v[92:95]
	v_mfma_f32_16x16x32_bf16 v[96:99], v[28:31], v[188:191], v[96:99]
	v_mfma_f32_16x16x32_bf16 v[100:103], v[28:31], v[204:207], v[100:103]
	v_mfma_f32_16x16x32_bf16 v[104:107], v[44:47], v[148:151], v[104:107]
	v_mfma_f32_16x16x32_bf16 v[108:111], v[44:47], v[164:167], v[108:111]
	v_mfma_f32_16x16x32_bf16 v[112:115], v[44:47], v[188:191], v[112:115]
	v_mfma_f32_16x16x32_bf16 v[116:119], v[44:47], v[204:207], v[116:119]
	v_mfma_f32_16x16x32_bf16 v[120:123], v[60:63], v[148:151], v[120:123]
	v_mfma_f32_16x16x32_bf16 v[124:127], v[60:63], v[164:167], v[124:127]
	v_mfma_f32_16x16x32_bf16 v[128:131], v[60:63], v[188:191], v[128:131]
	v_mfma_f32_16x16x32_bf16 v[132:135], v[60:63], v[204:207], v[132:135]
	s_barrier
	ds_write_b128 v220, v[72:75]
	ds_write_b128 v220, v[76:79] offset:1024
	ds_write_b128 v220, v[80:83] offset:2048
	ds_write_b128 v220, v[84:87] offset:3072
	ds_write_b128 v220, v[88:91] offset:4096
	ds_write_b128 v220, v[92:95] offset:5120
	ds_write_b128 v220, v[96:99] offset:6144
	ds_write_b128 v220, v[100:103] offset:7168
	ds_write_b128 v220, v[104:107] offset:8192
	ds_write_b128 v220, v[108:111] offset:9216
	ds_write_b128 v220, v[112:115] offset:10240
	ds_write_b128 v220, v[116:119] offset:11264
	ds_write_b128 v220, v[120:123] offset:12288
	ds_write_b128 v220, v[124:127] offset:13312
	ds_write_b128 v220, v[128:131] offset:14336
	ds_write_b128 v220, v[132:135] offset:15360
	s_waitcnt lgkmcnt(0)
	s_barrier
	ds_read_b128 v[56:59], v177
	ds_read_b128 v[60:63], v177 offset:1024
	ds_read_b128 v[48:51], v177 offset:16384
	ds_read_b128 v[52:55], v177 offset:17408
	ds_read_b128 v[40:43], v177 offset:32768
	ds_read_b128 v[44:47], v177 offset:33792
	ds_read_b128 v[0:3], v177 offset:49152
	ds_read_b128 v[4:7], v177 offset:50176
	ds_read_b128 v[8:11], v212
	ds_read_b128 v[12:15], v213
	ds_read_b128 v[16:19], v214
	ds_read_b128 v[20:23], v215
	ds_read_b128 v[24:27], v216
	ds_read_b128 v[28:31], v217
	ds_read_b128 v[32:35], v218
	ds_read_b128 v[36:39], v219
	s_lshl_b32 s0, s36, 4
	s_and_b32 s0, s0, 0xc0
	s_or_b32 s0, s38, s0
	v_lshrrev_b32_e32 v184, 2, v211
	v_and_b32_e32 v184, 0x30, v184
	v_or3_b32 v66, v184, v210, s0
	v_cmp_lt_i32_e64 s[0:1], s29, v66
	s_and_saveexec_b64 s[2:3], s[0:1]
	s_xor_b64 s[0:1], exec, s[2:3]
	s_cbranch_execz .LBB0_1128
	v_add_u32_e32 v182, 0xffffc000, v66
	v_readlane_b32 s40, v250, 7
	v_lshlrev_b64 v[68:69], 12, v[182:183]
	v_readlane_b32 s42, v250, 9
	v_readlane_b32 s43, v250, 10
	v_readlane_b32 s41, v250, 8
	v_readlane_b32 s44, v250, 11
	v_readlane_b32 s45, v250, 12
	v_readlane_b32 s46, v250, 13
	v_readlane_b32 s47, v250, 14
	v_readlane_b32 s48, v250, 15
	v_readlane_b32 s49, v250, 16
	v_readlane_b32 s50, v250, 17
	v_readlane_b32 s51, v250, 18
	v_readlane_b32 s52, v250, 19
	v_readlane_b32 s53, v250, 20
	v_readlane_b32 s54, v250, 21
	v_readlane_b32 s55, v250, 22
	v_lshl_add_u64 v[70:71], s[42:43], 0, v[68:69]
	v_mov_b32_e32 v67, v183

.LBB0_1130:
	s_or_b64 exec, exec, s[0:1]
	v_and_b32_e32 v184, 0x2f, v211
	v_lshl_add_u32 v68, s37, 8, v184
	s_lshl_b32 s64, s36, 6
	s_and_b32 s64, s64, 0xc0
	v_add_u32_e32 v68, s64, v68
	v_ashrrev_i32_e32 v69, 31, v68
	v_lshl_add_u64 v[70:71], v[68:69], 2, v[70:71]
	global_load_dword v72, v[70:71], off
	global_load_dword v73, v[70:71], off offset:64
	s_waitcnt lgkmcnt(14)
	v_pk_add_f32 v[60:61], v[60:61], 0 op_sel_hi:[1,0]
	v_pk_add_f32 v[56:57], v[56:57], 0 op_sel_hi:[1,0]
	s_waitcnt lgkmcnt(12)
	v_pk_add_f32 v[52:53], v[60:61], v[52:53]
	v_pk_add_f32 v[48:49], v[56:57], v[48:49]
	s_waitcnt lgkmcnt(10)
	v_pk_add_f32 v[44:45], v[52:53], v[44:45]
	v_pk_add_f32 v[40:41], v[48:49], v[40:41]
	s_waitcnt lgkmcnt(8)
	v_pk_add_f32 v[4:5], v[44:45], v[4:5]
	v_pk_add_f32 v[0:1], v[40:41], v[0:1]
	s_waitcnt lgkmcnt(6)
	v_pk_add_f32 v[4:5], v[4:5], v[12:13]
	v_pk_add_f32 v[0:1], v[0:1], v[8:9]
	s_waitcnt lgkmcnt(4)
	v_pk_add_f32 v[4:5], v[4:5], v[20:21]
	v_pk_add_f32 v[0:1], v[0:1], v[16:17]
	s_waitcnt lgkmcnt(2)
	v_pk_add_f32 v[8:9], v[4:5], v[28:29]
	v_pk_add_f32 v[0:1], v[0:1], v[24:25]
	s_waitcnt lgkmcnt(0)
	v_pk_add_f32 v[8:9], v[8:9], v[36:37]
	v_pk_add_f32 v[4:5], v[0:1], v[32:33]
	v_lshlrev_b64 v[70:71], 11, v[66:67]
	v_lshl_add_u64 v[56:57], s[16:17], 0, v[70:71]
	v_lshl_add_u64 v[48:49], v[68:69], 1, v[56:57]
	s_waitcnt vmcnt(1)
	v_add_f32_e32 v0, v4, v72
	s_waitcnt vmcnt(0)
	v_add_f32_e32 v1, v8, v73
	v_mul_f32_e32 v12, v1, v1
	v_bfe_u32 v4, v0, 16, 1
	v_fmac_f32_e32 v12, v0, v0
	v_add3_u32 v4, v0, v4, s30
	v_bfe_u32 v8, v1, 16, 1
	v_add_f32_dpp v0, v12, v12 quad_perm:[1,0,3,2] row_mask:0xf bank_mask:0xf bound_ctrl:1
	v_add3_u32 v1, v1, v8, s30
	global_store_short_d16_hi v[48:49], v4, off
	global_store_short_d16_hi v[48:49], v1, off offset:32
	v_add_f32_dpp v0, v0, v0 quad_perm:[2,3,0,1] row_mask:0xf bank_mask:0xf bound_ctrl:1
	s_nop 1
	v_add_f32_dpp v0, v0, v0 row_ror:4 row_mask:0xf bank_mask:0xf bound_ctrl:1
	s_nop 1
	v_mov_b32_dpp v1, v0 row_ror:8 row_mask:0xf bank_mask:0xf bound_ctrl:1
	s_and_saveexec_b64 s[0:1], vcc
	s_cbranch_execz .LBB0_1132
	v_lshl_add_u64 v[12:13], v[66:67], 2, s[92:93]
	v_add_f32_e32 v0, v0, v1
	global_atomic_add_f32 v[12:13], v0, off
